# P1 GEMM loop: A half-tile As[0][0]@t+2 DMA moved from SP2(t) load segment to SP1(t+1) (pieces 2/4/4/6 instead of 2/6/2/6), SP2 wait vmcnt 8->6
# baseline (speedup 1.0000x reference)
.LBB0_177:
	ds_read_b128 v[128:131], v171
	ds_read_b128 v[132:135], v171 offset:1024
	ds_read_b128 v[136:139], v171 offset:2048
	ds_read_b128 v[160:163], v171 offset:3072
	ds_read_b128 v[164:167], v172
	ds_read_b128 v[174:177], v172 offset:1024
	ds_read_b128 v[178:181], v172 offset:2048
	ds_read_b128 v[182:185], v172 offset:3072
	s_add_u32 s52, s44, 0xfffc0080
	s_addc_u32 s53, s45, -1
	s_cmp_eq_u32 s84, 12
	s_cselect_b32 s57, s7, s53
	s_cselect_b32 s56, s8, s52
	s_cselect_b32 s53, s27, s83
	s_cselect_b32 s52, s29, s43
	v_lshl_add_u64 v[198:199], s[44:45], 0, v[152:153]
	s_add_i32 m0, s33, 0xc000
	ds_read_b128 v[186:189], v173
	ds_read_b128 v[190:193], v173 offset:1024
	ds_read_b128 v[194:197], v173 offset:2048
	ds_read_b128 v[202:205], v173 offset:3072
	ds_read_b128 v[206:209], v173 offset:4096
	ds_read_b128 v[210:213], v173 offset:5120
	ds_read_b128 v[214:217], v173 offset:6144
	ds_read_b128 v[218:221], v173 offset:7168
	global_load_lds_dwordx4 v[198:199], off
	s_add_i32 m0, s33, 0xe000
	v_lshl_add_u64 v[198:199], s[44:45], 0, v[154:155]
	global_load_lds_dwordx4 v[198:199], off
	s_waitcnt vmcnt(8)
	s_waitcnt lgkmcnt(0)
	s_barrier
	s_waitcnt lgkmcnt(0)
	v_mfma_f32_16x16x32_bf16 v[124:127], v[128:131], v[186:189], v[124:127]
	v_mfma_f32_16x16x32_bf16 v[120:123], v[136:139], v[186:189], v[120:123]
	v_mfma_f32_16x16x32_bf16 v[112:115], v[128:131], v[194:197], v[112:115]
	v_mfma_f32_16x16x32_bf16 v[104:107], v[136:139], v[194:197], v[104:107]
	v_mfma_f32_16x16x32_bf16 v[100:103], v[128:131], v[206:209], v[100:103]
	v_mfma_f32_16x16x32_bf16 v[92:95], v[136:139], v[206:209], v[92:95]
	v_mfma_f32_16x16x32_bf16 v[84:87], v[128:131], v[214:217], v[84:87]
	v_mfma_f32_16x16x32_bf16 v[76:79], v[136:139], v[214:217], v[76:79]
	v_mfma_f32_16x16x32_bf16 v[124:127], v[132:135], v[190:193], v[124:127]
	v_mfma_f32_16x16x32_bf16 v[120:123], v[160:163], v[190:193], v[120:123]
	v_mfma_f32_16x16x32_bf16 v[112:115], v[132:135], v[202:205], v[112:115]
	v_mfma_f32_16x16x32_bf16 v[104:107], v[160:163], v[202:205], v[104:107]
	v_mfma_f32_16x16x32_bf16 v[100:103], v[132:135], v[210:213], v[100:103]
	v_mfma_f32_16x16x32_bf16 v[92:95], v[160:163], v[210:213], v[92:95]
	v_mfma_f32_16x16x32_bf16 v[84:87], v[132:135], v[218:221], v[84:87]
	v_mfma_f32_16x16x32_bf16 v[76:79], v[160:163], v[218:221], v[76:79]
	v_mfma_f32_16x16x32_bf16 v[116:119], v[164:167], v[186:189], v[116:119]
	v_mfma_f32_16x16x32_bf16 v[108:111], v[178:181], v[186:189], v[108:111]
	v_mfma_f32_16x16x32_bf16 v[96:99], v[164:167], v[194:197], v[96:99]
	v_mfma_f32_16x16x32_bf16 v[88:91], v[178:181], v[194:197], v[88:91]
	v_mfma_f32_16x16x32_bf16 v[80:83], v[164:167], v[206:209], v[80:83]
	v_mfma_f32_16x16x32_bf16 v[72:75], v[178:181], v[206:209], v[72:75]
	v_mfma_f32_16x16x32_bf16 v[68:71], v[164:167], v[214:217], v[68:71]
	v_mfma_f32_16x16x32_bf16 v[64:67], v[178:181], v[214:217], v[64:67]
	v_mfma_f32_16x16x32_bf16 v[116:119], v[174:177], v[190:193], v[116:119]
	v_mfma_f32_16x16x32_bf16 v[108:111], v[182:185], v[190:193], v[108:111]
	v_mfma_f32_16x16x32_bf16 v[96:99], v[174:177], v[202:205], v[96:99]
	v_mfma_f32_16x16x32_bf16 v[88:91], v[182:185], v[202:205], v[88:91]
	v_mfma_f32_16x16x32_bf16 v[80:83], v[174:177], v[210:213], v[80:83]
	v_mfma_f32_16x16x32_bf16 v[72:75], v[182:185], v[210:213], v[72:75]
	v_mfma_f32_16x16x32_bf16 v[68:71], v[174:177], v[218:221], v[68:71]
	v_mfma_f32_16x16x32_bf16 v[64:67], v[182:185], v[218:221], v[64:67]
	s_barrier
	s_add_i32 s85, s80, s3
	v_lshl_add_u64 v[198:199], s[52:53], 0, v[142:143]
	s_mov_b32 m0, s85
	ds_read_b128 v[186:189], v173 offset:16384
	ds_read_b128 v[190:193], v173 offset:17408
	ds_read_b128 v[194:197], v173 offset:18432
	ds_read_b128 v[202:205], v173 offset:19456
	ds_read_b128 v[206:209], v173 offset:20480
	ds_read_b128 v[210:213], v173 offset:21504
	ds_read_b128 v[214:217], v173 offset:22528
	ds_read_b128 v[218:221], v173 offset:23552
	global_load_lds_dwordx4 v[198:199], off
	s_add_i32 m0, s85, 0x2000
	s_add_u32 s86, s52, 0x40000
	v_lshl_add_u64 v[200:201], s[52:53], 0, v[146:147]
	s_addc_u32 s87, s53, 0
	s_add_i32 s85, s81, s3
	global_load_lds_dwordx4 v[200:201], off
	v_lshl_add_u64 v[222:223], s[86:87], 0, v[142:143]
	s_mov_b32 m0, s85
	v_lshl_add_u64 v[224:225], s[56:57], 0, v[144:145]
	global_load_lds_dwordx4 v[222:223], off
	s_add_i32 m0, s85, 0x2000
	v_lshl_add_u64 v[222:223], s[86:87], 0, v[146:147]
	global_load_lds_dwordx4 v[222:223], off
	v_lshl_add_u64 v[222:223], s[56:57], 0, v[140:141]
	s_waitcnt vmcnt(6)
	s_waitcnt lgkmcnt(0)
	s_barrier
	s_waitcnt lgkmcnt(0)
	v_mfma_f32_16x16x32_bf16 v[60:63], v[128:131], v[186:189], v[60:63]
	v_mfma_f32_16x16x32_bf16 v[56:59], v[136:139], v[186:189], v[56:59]
	v_mfma_f32_16x16x32_bf16 v[52:55], v[128:131], v[194:197], v[52:55]
	v_mfma_f32_16x16x32_bf16 v[44:47], v[136:139], v[194:197], v[44:47]
	v_mfma_f32_16x16x32_bf16 v[36:39], v[128:131], v[206:209], v[36:39]
	v_mfma_f32_16x16x32_bf16 v[28:31], v[136:139], v[206:209], v[28:31]
	v_mfma_f32_16x16x32_bf16 v[20:23], v[128:131], v[214:217], v[20:23]
	v_mfma_f32_16x16x32_bf16 v[12:15], v[136:139], v[214:217], v[12:15]
	v_mfma_f32_16x16x32_bf16 v[60:63], v[132:135], v[190:193], v[60:63]
	v_mfma_f32_16x16x32_bf16 v[56:59], v[160:163], v[190:193], v[56:59]
	v_mfma_f32_16x16x32_bf16 v[52:55], v[132:135], v[202:205], v[52:55]
	v_mfma_f32_16x16x32_bf16 v[44:47], v[160:163], v[202:205], v[44:47]
	v_mfma_f32_16x16x32_bf16 v[36:39], v[132:135], v[210:213], v[36:39]
	v_mfma_f32_16x16x32_bf16 v[28:31], v[160:163], v[210:213], v[28:31]
	v_mfma_f32_16x16x32_bf16 v[20:23], v[132:135], v[218:221], v[20:23]
	v_mfma_f32_16x16x32_bf16 v[12:15], v[160:163], v[218:221], v[12:15]
	v_mfma_f32_16x16x32_bf16 v[48:51], v[164:167], v[186:189], v[48:51]
	v_mfma_f32_16x16x32_bf16 v[40:43], v[178:181], v[186:189], v[40:43]
	v_mfma_f32_16x16x32_bf16 v[32:35], v[164:167], v[194:197], v[32:35]
	v_mfma_f32_16x16x32_bf16 v[24:27], v[178:181], v[194:197], v[24:27]
	v_mfma_f32_16x16x32_bf16 v[16:19], v[164:167], v[206:209], v[16:19]
	v_mfma_f32_16x16x32_bf16 v[8:11], v[178:181], v[206:209], v[8:11]
	v_mfma_f32_16x16x32_bf16 v[4:7], v[164:167], v[214:217], v[4:7]
	v_mfma_f32_16x16x32_bf16 v[0:3], v[178:181], v[214:217], v[0:3]
	v_mfma_f32_16x16x32_bf16 v[48:51], v[174:177], v[190:193], v[48:51]
	v_mfma_f32_16x16x32_bf16 v[40:43], v[182:185], v[190:193], v[40:43]
	v_mfma_f32_16x16x32_bf16 v[32:35], v[174:177], v[202:205], v[32:35]
	v_mfma_f32_16x16x32_bf16 v[24:27], v[182:185], v[202:205], v[24:27]
	v_mfma_f32_16x16x32_bf16 v[16:19], v[174:177], v[210:213], v[16:19]
	v_mfma_f32_16x16x32_bf16 v[8:11], v[182:185], v[210:213], v[8:11]
	v_mfma_f32_16x16x32_bf16 v[4:7], v[174:177], v[218:221], v[4:7]
	v_mfma_f32_16x16x32_bf16 v[0:3], v[182:185], v[218:221], v[0:3]
	s_barrier
	s_add_i32 s85, 0, 0x18000
	v_add_u32_e32 v148, s85, v169
	s_add_i32 s86, 0, 0x1c000
	ds_read_b128 v[128:131], v148
	ds_read_b128 v[132:135], v148 offset:1024
	ds_read_b128 v[136:139], v148 offset:2048
	ds_read_b128 v[160:163], v148 offset:3072
	v_add_u32_e32 v148, s86, v169
	ds_read_b128 v[164:167], v148
	ds_read_b128 v[174:177], v148 offset:1024
	ds_read_b128 v[178:181], v148 offset:2048
	ds_read_b128 v[182:185], v148 offset:3072
	s_mov_b32 m0, s33
	s_nop 0
	global_load_lds_dwordx4 v[222:223], off
	s_mov_b32 m0, s62
	s_nop 0
	global_load_lds_dwordx4 v[224:225], off
	s_add_u32 s56, s56, 0x40000
	s_addc_u32 s57, s57, 0
	s_mov_b32 m0, s63
	v_lshl_add_u64 v[226:227], s[56:57], 0, v[140:141]
	ds_read_b128 v[186:189], v173 offset:32768
	ds_read_b128 v[190:193], v173 offset:33792
	ds_read_b128 v[194:197], v173 offset:34816
	ds_read_b128 v[202:205], v173 offset:35840
	ds_read_b128 v[206:209], v173 offset:36864
	ds_read_b128 v[210:213], v173 offset:37888
	ds_read_b128 v[214:217], v173 offset:38912
	ds_read_b128 v[218:221], v173 offset:39936
	global_load_lds_dwordx4 v[226:227], off
	s_mov_b32 m0, s64
	v_lshl_add_u64 v[226:227], s[56:57], 0, v[144:145]
	global_load_lds_dwordx4 v[226:227], off
	s_waitcnt vmcnt(8)
	s_waitcnt lgkmcnt(0)
	s_barrier
	s_waitcnt lgkmcnt(0)
	v_mfma_f32_16x16x32_bf16 v[124:127], v[128:131], v[186:189], v[124:127]
	v_mfma_f32_16x16x32_bf16 v[120:123], v[136:139], v[186:189], v[120:123]
	v_mfma_f32_16x16x32_bf16 v[112:115], v[128:131], v[194:197], v[112:115]
	v_mfma_f32_16x16x32_bf16 v[104:107], v[136:139], v[194:197], v[104:107]
	v_mfma_f32_16x16x32_bf16 v[100:103], v[128:131], v[206:209], v[100:103]
	v_mfma_f32_16x16x32_bf16 v[92:95], v[136:139], v[206:209], v[92:95]
	v_mfma_f32_16x16x32_bf16 v[84:87], v[128:131], v[214:217], v[84:87]
	v_mfma_f32_16x16x32_bf16 v[76:79], v[136:139], v[214:217], v[76:79]
	v_mfma_f32_16x16x32_bf16 v[124:127], v[132:135], v[190:193], v[124:127]
	v_mfma_f32_16x16x32_bf16 v[120:123], v[160:163], v[190:193], v[120:123]
	v_mfma_f32_16x16x32_bf16 v[112:115], v[132:135], v[202:205], v[112:115]
	v_mfma_f32_16x16x32_bf16 v[104:107], v[160:163], v[202:205], v[104:107]
	v_mfma_f32_16x16x32_bf16 v[100:103], v[132:135], v[210:213], v[100:103]
	v_mfma_f32_16x16x32_bf16 v[92:95], v[160:163], v[210:213], v[92:95]
	v_mfma_f32_16x16x32_bf16 v[84:87], v[132:135], v[218:221], v[84:87]
	v_mfma_f32_16x16x32_bf16 v[76:79], v[160:163], v[218:221], v[76:79]
	v_mfma_f32_16x16x32_bf16 v[116:119], v[164:167], v[186:189], v[116:119]
	v_mfma_f32_16x16x32_bf16 v[108:111], v[178:181], v[186:189], v[108:111]
	v_mfma_f32_16x16x32_bf16 v[96:99], v[164:167], v[194:197], v[96:99]
	v_mfma_f32_16x16x32_bf16 v[88:91], v[178:181], v[194:197], v[88:91]
	v_mfma_f32_16x16x32_bf16 v[80:83], v[164:167], v[206:209], v[80:83]
	v_mfma_f32_16x16x32_bf16 v[72:75], v[178:181], v[206:209], v[72:75]
	v_mfma_f32_16x16x32_bf16 v[68:71], v[164:167], v[214:217], v[68:71]
	v_mfma_f32_16x16x32_bf16 v[64:67], v[178:181], v[214:217], v[64:67]
	v_mfma_f32_16x16x32_bf16 v[116:119], v[174:177], v[190:193], v[116:119]
	v_mfma_f32_16x16x32_bf16 v[108:111], v[182:185], v[190:193], v[108:111]
	v_mfma_f32_16x16x32_bf16 v[96:99], v[174:177], v[202:205], v[96:99]
	v_mfma_f32_16x16x32_bf16 v[88:91], v[182:185], v[202:205], v[88:91]
	v_mfma_f32_16x16x32_bf16 v[80:83], v[174:177], v[210:213], v[80:83]
	v_mfma_f32_16x16x32_bf16 v[72:75], v[182:185], v[210:213], v[72:75]
	v_mfma_f32_16x16x32_bf16 v[68:71], v[174:177], v[218:221], v[68:71]
	v_mfma_f32_16x16x32_bf16 v[64:67], v[182:185], v[218:221], v[64:67]
	s_barrier
	s_add_i32 s56, s85, s3
	v_lshl_add_u64 v[198:199], v[198:199], 0, s[16:17]
	s_mov_b32 m0, s56
	ds_read_b128 v[186:189], v173 offset:49152
	ds_read_b128 v[190:193], v173 offset:50176
	ds_read_b128 v[194:197], v173 offset:51200
	ds_read_b128 v[202:205], v173 offset:52224
	ds_read_b128 v[206:209], v173 offset:53248
	ds_read_b128 v[210:213], v173 offset:54272
	ds_read_b128 v[214:217], v173 offset:55296
	ds_read_b128 v[218:221], v173 offset:56320
	global_load_lds_dwordx4 v[198:199], off
	s_add_i32 m0, s56, 0x2000
	s_add_u32 s52, s52, 0x40080
	v_lshl_add_u64 v[198:199], v[200:201], 0, s[16:17]
	s_addc_u32 s53, s53, 0
	s_add_i32 s56, s86, s3
	global_load_lds_dwordx4 v[198:199], off
	s_mov_b32 m0, s56
	v_lshl_add_u64 v[198:199], s[52:53], 0, v[142:143]
	global_load_lds_dwordx4 v[198:199], off
	s_add_i32 m0, s56, 0x2000
	v_lshl_add_u64 v[198:199], s[52:53], 0, v[146:147]
	global_load_lds_dwordx4 v[198:199], off
	s_mov_b32 m0, s69
	v_lshl_add_u64 v[198:199], v[222:223], 0, s[16:17]
	global_load_lds_dwordx4 v[198:199], off
	s_mov_b32 m0, s72
	v_lshl_add_u64 v[198:199], v[224:225], 0, s[16:17]
	global_load_lds_dwordx4 v[198:199], off
	s_waitcnt vmcnt(8)
	s_waitcnt lgkmcnt(0)
	s_barrier
	s_waitcnt lgkmcnt(0)
	v_mfma_f32_16x16x32_bf16 v[60:63], v[128:131], v[186:189], v[60:63]
	v_mfma_f32_16x16x32_bf16 v[56:59], v[136:139], v[186:189], v[56:59]
	v_mfma_f32_16x16x32_bf16 v[52:55], v[128:131], v[194:197], v[52:55]
	v_mfma_f32_16x16x32_bf16 v[44:47], v[136:139], v[194:197], v[44:47]
	v_mfma_f32_16x16x32_bf16 v[36:39], v[128:131], v[206:209], v[36:39]
	v_mfma_f32_16x16x32_bf16 v[28:31], v[136:139], v[206:209], v[28:31]
	v_mfma_f32_16x16x32_bf16 v[20:23], v[128:131], v[214:217], v[20:23]
	v_mfma_f32_16x16x32_bf16 v[12:15], v[136:139], v[214:217], v[12:15]
	v_mfma_f32_16x16x32_bf16 v[60:63], v[132:135], v[190:193], v[60:63]
	v_mfma_f32_16x16x32_bf16 v[56:59], v[160:163], v[190:193], v[56:59]
	v_mfma_f32_16x16x32_bf16 v[52:55], v[132:135], v[202:205], v[52:55]
	v_mfma_f32_16x16x32_bf16 v[44:47], v[160:163], v[202:205], v[44:47]
	v_mfma_f32_16x16x32_bf16 v[36:39], v[132:135], v[210:213], v[36:39]
	v_mfma_f32_16x16x32_bf16 v[28:31], v[160:163], v[210:213], v[28:31]
	v_mfma_f32_16x16x32_bf16 v[20:23], v[132:135], v[218:221], v[20:23]
	v_mfma_f32_16x16x32_bf16 v[12:15], v[160:163], v[218:221], v[12:15]
	v_mfma_f32_16x16x32_bf16 v[48:51], v[164:167], v[186:189], v[48:51]
	v_mfma_f32_16x16x32_bf16 v[40:43], v[178:181], v[186:189], v[40:43]
	v_mfma_f32_16x16x32_bf16 v[32:35], v[164:167], v[194:197], v[32:35]
	v_mfma_f32_16x16x32_bf16 v[24:27], v[178:181], v[194:197], v[24:27]
	v_mfma_f32_16x16x32_bf16 v[16:19], v[164:167], v[206:209], v[16:19]
	v_mfma_f32_16x16x32_bf16 v[8:11], v[178:181], v[206:209], v[8:11]
	v_mfma_f32_16x16x32_bf16 v[4:7], v[164:167], v[214:217], v[4:7]
	v_mfma_f32_16x16x32_bf16 v[0:3], v[178:181], v[214:217], v[0:3]
	v_mfma_f32_16x16x32_bf16 v[48:51], v[174:177], v[190:193], v[48:51]
	v_mfma_f32_16x16x32_bf16 v[40:43], v[182:185], v[190:193], v[40:43]
	v_mfma_f32_16x16x32_bf16 v[32:35], v[174:177], v[202:205], v[32:35]
	v_mfma_f32_16x16x32_bf16 v[24:27], v[182:185], v[202:205], v[24:27]
	v_mfma_f32_16x16x32_bf16 v[16:19], v[174:177], v[210:213], v[16:19]
	v_mfma_f32_16x16x32_bf16 v[8:11], v[182:185], v[210:213], v[8:11]
	v_mfma_f32_16x16x32_bf16 v[4:7], v[174:177], v[218:221], v[4:7]
	v_mfma_f32_16x16x32_bf16 v[0:3], v[182:185], v[218:221], v[0:3]
	s_barrier
	s_add_i32 s84, s84, 2
	s_add_u32 s44, s44, 0x100
	s_addc_u32 s45, s45, 0
	s_add_u32 s43, s43, 0x100
	s_addc_u32 s83, s83, 0
	s_cmp_gt_u32 s84, 13
	s_cbranch_scc0 .LBB0_177
	s_and_b64 vcc, exec, s[18:19]
	s_cbranch_vccz .LBB0_180
	s_barrier
